# grid barriers: no s_sleep between release polls (each poll is already a memory round trip)
# speedup vs baseline: 1.0051x; 1.0051x over previous
.Lgbf_spin:
	global_atomic_add v2, v1, v10, s[86:87] sc0
	s_waitcnt vmcnt(0)
	v_readfirstlane_b32 s7, v2
	s_cmp_ge_u32 s7, s99
	s_cbranch_scc1 .Lgbf_acq
	s_sub_i32 s11, s11, 1
	s_cmp_lg_u32 s11, 0
	s_cbranch_scc1 .Lgbf_spin

.Lgb0_spin:
	global_atomic_add v2, v1, v10, s[8:9] sc0
	s_waitcnt vmcnt(0)
	v_readfirstlane_b32 s7, v2
	s_cmp_ge_u32 s7, s6
	s_cbranch_scc1 .Lgb0_acq
	s_sub_i32 s11, s11, 1
	s_cmp_lg_u32 s11, 0
	s_cbranch_scc1 .Lgb0_spin
